# adds GEMM phase prologue: K-tile-1 staging groups issued before the first wait (vmcnt 2 to 8), one HBM round trip less per GEMM phase
# baseline (speedup 1.0000x reference)
; DI int TIDX() { int t = (int)threadIdx.x; asm volatile("" : "+v"(t)); return t; }
; #define PG8_STAGE(bufoff, gbase, voff) do { _Pragma("unroll") for (int _i = 0; _i < 2; ++_i) \
;         __builtin_amdgcn_global_load_lds((const unsigned*)((const char*)(gbase) + (voff)[_i]), (PG8_LAS unsigned*)(lds + (bufoff) + ldsw + _i * 8192), 16, 0, 0); } while (0)
; #define PG8_WAIT_V(n) asm volatile("s_waitcnt vmcnt(" #n ")" ::: "memory")
; #define PG8_BAR __builtin_amdgcn_s_barrier()
; template <class Epi, class Sched, bool ALIGN_EPI = false, bool SP2 = false>
; __device__ __forceinline__ void gemm_phase(PG8_LAS unsigned char* lds, const Gemm g, const Sched& S, const Epi& E) {
;     const int tid = TIDX(), wid = __builtin_amdgcn_readfirstlane(tid >> 6), lane = tid & 63, wr = wid >> 2, wc = wid & 3, fr = lane & 15, fq = lane >> 4;
;     const int K = g.K, nt = K / BK;
;     unsigned voffA[2], voffB[2];
; #pragma unroll
;     for (int i = 0; i < 2; ++i) { int R, C; stage_rc(tid * 16 + i * 8192, R, C); const int Rb = E.perm ? ((R & ~31) + perm32(R & 31)) : R;
;         voffA[i] = (unsigned)(R * K + C) * 2u; voffB[i] = (unsigned)(Rb * K + C) * 2u; }
;     const size_t kstep = (size_t)(BK * 2);
;     const size_t hstep = (size_t)HALF * K * 2;
;     const size_t tstep = 2 * hstep;
;     const unsigned ldsw = (unsigned)wid * 1024u;
;     const int aoff = lds_byte(wr * 64 + fr, fq * 8), boff = lds_byte(wc * 32 + fr, fq * 8);
;     ...
;     if constexpr (SP2) {
;         PG8_STAGE(PG8_SB(0, 0), cB, voffB); PG8_STAGE(PG8_SB(0, 1), cB + hstep, voffB); PG8_STAGE(PG8_SA(0, 0), cA, voffA); PG8_STAGE(PG8_SA(0, 1), cA + hstep, voffA);
;         if (wr == 1) PG8_BAR;
;         PG8_WAIT_V(2); PG8_BAR;
;         PG8_STAGE(PG8_SB(1, 0), cB + kstep, voffB); PG8_STAGE(PG8_SA(1, 0), cA + kstep, voffA); PG8_STAGE(PG8_SB(1, 1), cB + hstep + kstep, voffB);
;         PG8_WAIT_V(6); PG8_BAR;
.LBB0_828:
	v_lshrrev_b32_e32 v20, 1, v17
	s_xor_b64 s[34:35], s[4:5], -1
	v_and_b32_e32 v20, 24, v20
	s_add_u32 s36, s14, 0x3540c400
	v_and_b32_e32 v19, 15, v17
	v_lshlrev_b32_e32 v21, 1, v20
	v_lshlrev_b32_e32 v17, 2, v17
	s_addc_u32 s37, s15, 0
	v_lshl_or_b32 v171, s7, 6, v19
	v_lshl_or_b32 v19, v19, 6, v21
	s_lshl_b32 s4, s7, 13
	v_and_b32_e32 v17, 32, v17
	v_bitop3_b32 v21, v19, s4, v17 bitop3:0xde
	s_lshl_b32 s4, s6, 5
	s_and_b32 s6, s4, 0x60
	s_lshl_b32 s4, s6, 7
	s_lshl_b32 s5, s73, 3
	v_bitop3_b32 v176, v19, s4, v17 bitop3:0xde
	s_lshl_b32 s4, s58, 5
	s_and_b32 s5, s5, 16
	s_or_b32 s4, s4, s5
	s_lshr_b32 s55, s25, 6
	s_mulk_i32 s4, 0x1800
	s_mov_b32 s5, s91
	s_add_i32 s56, s55, -2
	s_ashr_i32 s57, s44, 31
	s_lshl_b64 s[4:5], s[4:5], 2
	s_add_u32 s4, s14, s4
	s_addc_u32 s5, s15, s5
	s_add_u32 s58, s4, 0xc000
	s_addc_u32 s59, s5, 0
	s_add_i32 m0, s51, 0x18000
	v_lshl_add_u64 v[0:1], v[0:1], 0, s[82:83]
	global_load_lds_dwordx4 v[0:1], off
	v_lshl_add_u64 v[0:1], v[2:3], 0, s[82:83]
	s_add_i32 m0, s51, 0x1a000
	s_add_i32 s60, s51, 0x8000
	global_load_lds_dwordx4 v[0:1], off
	v_lshl_add_u64 v[0:1], v[8:9], 0, s[82:83]
	s_mov_b32 m0, s60
	s_add_i32 s61, s51, 0xa000
	global_load_lds_dwordx4 v[0:1], off
	v_lshl_add_u64 v[0:1], v[10:11], 0, s[82:83]
	s_mov_b32 m0, s61
	s_mov_b32 s25, s91
	global_load_lds_dwordx4 v[0:1], off
	s_add_i32 m0, s51, 0x1c000
	v_lshl_add_u64 v[0:1], v[4:5], 0, s[82:83]
	global_load_lds_dwordx4 v[0:1], off
	v_lshl_add_u64 v[0:1], v[6:7], 0, s[82:83]
	s_add_i32 m0, s51, 0x1e000
	s_cmpk_lt_u32 s8, 0x100
	global_load_lds_dwordx4 v[0:1], off
	s_cselect_b64 s[14:15], -1, 0
	s_abs_i32 s63, s47
	v_cvt_f32_u32_e32 v0, s63
	s_sub_i32 s4, 0, s63
	v_mov_b32_e32 v1, v169
	s_waitcnt vmcnt(8)
	s_barrier
	s_waitcnt vmcnt(6)
	v_rcp_iflag_f32_e32 v0, v0
	v_or_b32_e32 v177, s6, v20
	s_ashr_i32 s62, s47, 31
	s_mov_b32 s64, 0
	v_mul_f32_e32 v0, 0x4f7ffffe, v0
	v_cvt_u32_f32_e32 v0, v0
	v_add_u32_e32 v178, 32, v21
	s_barrier
	v_readfirstlane_b32 s5, v0
	v_add_u32_e32 v0, v14, v12
	v_add_lshl_u32 v0, v0, v13, 1
	s_mul_i32 s4, s4, s5
	v_lshl_add_u64 v[158:159], s[90:91], 0, v[0:1]
	v_add_u32_e32 v0, v18, v15
	s_mul_hi_u32 s4, s5, s4
	v_add_lshl_u32 v0, v0, v16, 1
	s_add_i32 s65, s5, s4
	v_lshl_add_u64 v[160:161], s[90:91], 0, v[0:1]
	s_branch .LBB0_831
